# hand-written residual epilogue for out-proj AB GEMM (scalar row-pointer math per 16-row group, 64 loads in flight)
# speedup vs baseline: 1.4372x; 1.4372x over previous
.LBB0_782:
	s_ashr_i32 s0, s93, 31
	v_readlane_b32 s1, v250, 36
	s_xor_b32 s0, s0, s1
	s_abs_i32 s1, s93
	v_readlane_b32 s2, v250, 39
	s_mul_hi_u32 s2, s1, s2
	v_readlane_b32 s5, v250, 38
	s_mul_i32 s3, s2, s5
	s_sub_i32 s1, s1, s3
	s_add_i32 s3, s2, 1
	s_sub_i32 s4, s1, s5
	s_cmp_ge_u32 s1, s5
	s_cselect_b32 s2, s3, s2
	s_cselect_b32 s1, s4, s1
	s_add_i32 s3, s2, 1
	s_cmp_ge_u32 s1, s5
	s_cselect_b32 s1, s3, s2
	s_xor_b32 s1, s1, s0
	s_sub_i32 s0, s1, s0
	s_lshl_b32 s0, s0, 3
	v_readlane_b32 s1, v250, 37
	s_mul_i32 s1, s1, s0
	s_and_b32 s2, s93, 7
	s_add_i32 s1, s93, s1
	s_or_b32 s0, s0, s2
	s_lshr_b32 s1, s1, 3
	s_lshl_b32 s4, s0, 7
	v_readlane_b32 s0, v252, 40
	s_add_i32 s1, s1, s0
	v_mov_b32_e32 v84, v218
	s_lshl_b32 s0, s1, 7
	v_readlane_b32 s2, v250, 17
	s_waitcnt vmcnt(3)
	v_ashrrev_i32_e32 v3, 3, v84
	v_add_u32_e32 v0, s0, v3
	v_ashrrev_i32_e32 v1, 31, v0
	v_lshlrev_b64 v[0:1], 11, v[0:1]
	v_readlane_b32 s3, v250, 18
	v_lshlrev_b32_e32 v4, 4, v84
	v_and_b32_e32 v64, 0x70, v4
	v_lshl_add_u64 v[0:1], s[2:3], 0, v[0:1]
	v_lshl_add_u64 v[66:67], v[0:1], 0, v[64:65]
	v_add_u32_e32 v0, s4, v3
	v_ashrrev_i32_e32 v1, 31, v0
	v_readlane_b32 s2, v252, 6
	v_lshlrev_b64 v[0:1], 11, v[0:1]
	v_readlane_b32 s3, v252, 7
	s_mov_b32 s1, 0x10000
	v_add_co_u32_e32 v70, vcc, s1, v66
	v_lshl_add_u64 v[0:1], s[2:3], 0, v[0:1]
	v_lshl_add_u64 v[68:69], v[0:1], 0, v[64:65]
	v_lshrrev_b32_e32 v0, 4, v84
	v_addc_co_u32_e32 v71, vcc, 0, v67, vcc
	s_mov_b32 s2, 0x20000
	v_xor_b32_e32 v0, v0, v84
	v_ashrrev_i32_e32 v1, 1, v84
	v_add_co_u32_e32 v72, vcc, s2, v66
	v_and_b32_e32 v85, 31, v84
	v_lshlrev_b32_e32 v0, 4, v0
	v_and_b32_e32 v64, 0xffffffc0, v1
	v_addc_co_u32_e32 v73, vcc, 0, v67, vcc
	s_mov_b32 s3, 0x30000
	v_and_b32_e32 v0, 0x70, v0
	v_or_b32_e32 v1, v64, v85
	v_add_co_u32_e32 v74, vcc, s3, v66
	v_lshrrev_b32_e32 v2, 5, v84
	v_bfe_u32 v86, v84, 5, 1
	v_lshl_or_b32 v87, v3, 7, v0
	v_bfe_u32 v0, v84, 1, 3
	v_lshlrev_b32_e32 v32, 7, v1
	v_lshlrev_b32_e32 v1, 7, v84
	v_addc_co_u32_e32 v75, vcc, 0, v67, vcc
	v_and_b32_e32 v33, 0x2f80, v1
	v_bitop3_b32 v34, v2, v0, 1 bitop3:0x6c
	v_bitop3_b32 v35, v86, v0, 2 bitop3:0x36
	v_bitop3_b32 v36, v86, v0, 4 bitop3:0x36
	v_bitop3_b32 v37, v86, v0, 6 bitop3:0x36
	global_load_dwordx4 v[0:3], v[66:67], off
	global_load_dwordx4 v[4:7], v[70:71], off
	global_load_dwordx4 v[8:11], v[72:73], off
	global_load_dwordx4 v[12:15], v[74:75], off
	global_load_dwordx4 v[16:19], v[68:69], off
	v_add_co_u32_e32 v76, vcc, s1, v68
	s_nop 1
	v_addc_co_u32_e32 v77, vcc, 0, v69, vcc
	v_add_co_u32_e32 v78, vcc, s2, v68
	global_load_dwordx4 v[20:23], v[76:77], off
	s_nop 0
	v_addc_co_u32_e32 v79, vcc, 0, v69, vcc
	global_load_dwordx4 v[24:27], v[78:79], off
	v_add_co_u32_e32 v82, vcc, s3, v68
	s_nop 1
	v_addc_co_u32_e32 v83, vcc, 0, v69, vcc
	global_load_dwordx4 v[28:31], v[82:83], off
	global_load_dwordx4 v[96:99], v[66:67], off offset:128
	global_load_dwordx4 v[100:103], v[70:71], off offset:128
	global_load_dwordx4 v[104:107], v[72:73], off offset:128
	global_load_dwordx4 v[108:111], v[74:75], off offset:128
	global_load_dwordx4 v[112:115], v[68:69], off offset:128
	global_load_dwordx4 v[116:119], v[76:77], off offset:128
	global_load_dwordx4 v[120:123], v[78:79], off offset:128
	global_load_dwordx4 v[124:127], v[82:83], off offset:128
	s_waitcnt vmcnt(15)
	ds_write_b128 v87, v[0:3]
	s_waitcnt vmcnt(14)
	ds_write_b128 v87, v[4:7] offset:4096
	s_waitcnt vmcnt(13)
	ds_write_b128 v87, v[8:11] offset:8192
	s_waitcnt vmcnt(12)
	ds_write_b128 v87, v[12:15] offset:12288
	s_waitcnt vmcnt(11)
	ds_write_b128 v87, v[16:19] offset:32768
	s_waitcnt vmcnt(10)
	ds_write_b128 v87, v[20:23] offset:36864
	s_waitcnt vmcnt(9)
	ds_write_b128 v87, v[24:27] offset:40960
	s_waitcnt vmcnt(8)
	ds_write_b128 v87, v[28:31] offset:45056
	s_waitcnt lgkmcnt(0)
	s_barrier
	global_load_dwordx4 v[128:131], v[66:67], off offset:256
	global_load_dwordx4 v[132:135], v[70:71], off offset:256
	global_load_dwordx4 v[136:139], v[72:73], off offset:256
	global_load_dwordx4 v[140:143], v[74:75], off offset:256
	global_load_dwordx4 v[144:147], v[68:69], off offset:256
	global_load_dwordx4 v[148:151], v[76:77], off offset:256
	global_load_dwordx4 v[152:155], v[78:79], off offset:256
	global_load_dwordx4 v[156:159], v[82:83], off offset:256
	v_lshlrev_b32_e32 v0, 4, v34
	v_or_b32_e32 v94, v32, v0
	v_or_b32_e32 v95, v33, v0
	v_lshlrev_b32_e32 v0, 4, v35
	v_or_b32_e32 v92, v32, v0
	v_or_b32_e32 v93, v33, v0
	v_lshlrev_b32_e32 v0, 4, v36
	v_or_b32_e32 v90, v32, v0
	v_or_b32_e32 v91, v33, v0
	v_lshlrev_b32_e32 v0, 4, v37
	v_or_b32_e32 v88, v32, v0
	v_or_b32_e32 v89, v33, v0
	ds_read_b128 v[0:3], v94
	ds_read_b128 v[4:7], v95 offset:32768
	ds_read_b128 v[8:11], v94 offset:4096
	ds_read_b128 v[12:15], v95 offset:36864
	ds_read_b128 v[160:163], v92
	ds_read_b128 v[164:167], v93 offset:32768
	ds_read_b128 v[174:177], v92 offset:4096
	ds_read_b128 v[178:181], v93 offset:36864
	s_waitcnt lgkmcnt(6)
	v_mfma_f32_32x32x16_bf16 v[48:63], v[0:3], v[4:7], 0
	s_waitcnt lgkmcnt(4)
	v_mfma_f32_32x32x16_bf16 v[32:47], v[0:3], v[12:15], 0
	v_mfma_f32_32x32x16_bf16 v[16:31], v[8:11], v[4:7], 0
	v_mfma_f32_32x32x16_bf16 v[0:15], v[8:11], v[12:15], 0
	s_waitcnt lgkmcnt(2)
	v_mfma_f32_32x32x16_bf16 v[48:63], v[160:163], v[164:167], v[48:63]
	s_waitcnt lgkmcnt(0)
	v_mfma_f32_32x32x16_bf16 v[32:47], v[160:163], v[178:181], v[32:47]
	v_mfma_f32_32x32x16_bf16 v[16:31], v[174:177], v[164:167], v[16:31]
	v_mfma_f32_32x32x16_bf16 v[0:15], v[174:177], v[178:181], v[0:15]
	ds_read_b128 v[160:163], v90
	ds_read_b128 v[164:167], v91 offset:32768
	ds_read_b128 v[174:177], v90 offset:4096
	ds_read_b128 v[178:181], v91 offset:36864
	s_waitcnt lgkmcnt(2)
	v_mfma_f32_32x32x16_bf16 v[48:63], v[160:163], v[164:167], v[48:63]
	s_waitcnt lgkmcnt(0)
	v_mfma_f32_32x32x16_bf16 v[32:47], v[160:163], v[178:181], v[32:47]
	v_mfma_f32_32x32x16_bf16 v[16:31], v[174:177], v[164:167], v[16:31]
	v_mfma_f32_32x32x16_bf16 v[0:15], v[174:177], v[178:181], v[0:15]
	ds_read_b128 v[160:163], v88
	ds_read_b128 v[164:167], v89 offset:32768
	ds_read_b128 v[174:177], v88 offset:4096
	ds_read_b128 v[178:181], v89 offset:36864
	s_waitcnt vmcnt(15)
	ds_write_b128 v87, v[96:99] offset:16384
	s_waitcnt vmcnt(14)
	ds_write_b128 v87, v[100:103] offset:20480
	s_waitcnt vmcnt(13)
	ds_write_b128 v87, v[104:107] offset:24576
	s_waitcnt vmcnt(12)
	ds_write_b128 v87, v[108:111] offset:28672
	s_waitcnt vmcnt(11)
	ds_write_b128 v87, v[112:115] offset:49152
	s_waitcnt vmcnt(10)
	ds_write_b128 v87, v[116:119] offset:53248
	s_waitcnt vmcnt(9)
	ds_write_b128 v87, v[120:123] offset:57344
	s_waitcnt vmcnt(8)
	ds_write_b128 v87, v[124:127] offset:61440
	s_waitcnt lgkmcnt(0)
	s_barrier
	global_load_dwordx4 v[96:99], v[70:71], off offset:384
	global_load_dwordx4 v[100:103], v[72:73], off offset:384
	global_load_dwordx4 v[104:107], v[66:67], off offset:384
	global_load_dwordx4 v[108:111], v[68:69], off offset:384
	global_load_dwordx4 v[112:115], v[74:75], off offset:384
	global_load_dwordx4 v[116:119], v[76:77], off offset:384
	global_load_dwordx4 v[120:123], v[78:79], off offset:384
	global_load_dwordx4 v[124:127], v[82:83], off offset:384
	v_mfma_f32_32x32x16_bf16 v[48:63], v[160:163], v[164:167], v[48:63]
	v_mfma_f32_32x32x16_bf16 v[32:47], v[160:163], v[178:181], v[32:47]
	v_mfma_f32_32x32x16_bf16 v[16:31], v[174:177], v[164:167], v[16:31]
	v_mfma_f32_32x32x16_bf16 v[0:15], v[174:177], v[178:181], v[0:15]
	ds_read_b128 v[160:163], v94 offset:16384
	ds_read_b128 v[164:167], v95 offset:49152
	ds_read_b128 v[174:177], v94 offset:20480
	ds_read_b128 v[178:181], v95 offset:53248
	s_waitcnt lgkmcnt(2)
	v_mfma_f32_32x32x16_bf16 v[48:63], v[160:163], v[164:167], v[48:63]
	s_waitcnt lgkmcnt(0)
	v_mfma_f32_32x32x16_bf16 v[32:47], v[160:163], v[178:181], v[32:47]
	v_mfma_f32_32x32x16_bf16 v[16:31], v[174:177], v[164:167], v[16:31]
	v_mfma_f32_32x32x16_bf16 v[0:15], v[174:177], v[178:181], v[0:15]
	ds_read_b128 v[160:163], v92 offset:16384
	ds_read_b128 v[164:167], v93 offset:49152
	ds_read_b128 v[174:177], v92 offset:20480
	ds_read_b128 v[178:181], v93 offset:53248
	s_waitcnt lgkmcnt(2)
	v_mfma_f32_32x32x16_bf16 v[48:63], v[160:163], v[164:167], v[48:63]
	s_waitcnt lgkmcnt(0)
	v_mfma_f32_32x32x16_bf16 v[32:47], v[160:163], v[178:181], v[32:47]
	v_mfma_f32_32x32x16_bf16 v[16:31], v[174:177], v[164:167], v[16:31]
	v_mfma_f32_32x32x16_bf16 v[0:15], v[174:177], v[178:181], v[0:15]
	ds_read_b128 v[160:163], v90 offset:16384
	ds_read_b128 v[164:167], v91 offset:49152
	ds_read_b128 v[174:177], v90 offset:20480
	ds_read_b128 v[178:181], v91 offset:53248
	s_waitcnt lgkmcnt(2)
	v_mfma_f32_32x32x16_bf16 v[48:63], v[160:163], v[164:167], v[48:63]
	s_waitcnt lgkmcnt(0)
	v_mfma_f32_32x32x16_bf16 v[32:47], v[160:163], v[178:181], v[32:47]
	v_mfma_f32_32x32x16_bf16 v[16:31], v[174:177], v[164:167], v[16:31]
	v_mfma_f32_32x32x16_bf16 v[0:15], v[174:177], v[178:181], v[0:15]
	ds_read_b128 v[160:163], v88 offset:16384
	ds_read_b128 v[164:167], v89 offset:49152
	ds_read_b128 v[174:177], v88 offset:20480
	ds_read_b128 v[178:181], v89 offset:53248
	s_waitcnt vmcnt(15)
	ds_write_b128 v87, v[128:131]
	s_waitcnt vmcnt(14)
	ds_write_b128 v87, v[132:135] offset:4096
	s_waitcnt vmcnt(13)
	ds_write_b128 v87, v[136:139] offset:8192
	s_waitcnt vmcnt(12)
	ds_write_b128 v87, v[140:143] offset:12288
	s_waitcnt vmcnt(11)
	ds_write_b128 v87, v[144:147] offset:32768
	s_waitcnt vmcnt(10)
	ds_write_b128 v87, v[148:151] offset:36864
	s_waitcnt vmcnt(9)
	ds_write_b128 v87, v[152:155] offset:40960
	s_waitcnt vmcnt(8)
	ds_write_b128 v87, v[156:159] offset:45056
	s_waitcnt lgkmcnt(0)
	s_barrier
	global_load_dwordx4 v[128:131], v[70:71], off offset:512
	global_load_dwordx4 v[132:135], v[72:73], off offset:512
	global_load_dwordx4 v[136:139], v[66:67], off offset:512
	global_load_dwordx4 v[140:143], v[68:69], off offset:512
	global_load_dwordx4 v[144:147], v[74:75], off offset:512
	global_load_dwordx4 v[148:151], v[76:77], off offset:512
	global_load_dwordx4 v[152:155], v[78:79], off offset:512
	global_load_dwordx4 v[156:159], v[82:83], off offset:512
	v_mfma_f32_32x32x16_bf16 v[48:63], v[160:163], v[164:167], v[48:63]
	v_mfma_f32_32x32x16_bf16 v[32:47], v[160:163], v[178:181], v[32:47]
	v_mfma_f32_32x32x16_bf16 v[16:31], v[174:177], v[164:167], v[16:31]
	v_mfma_f32_32x32x16_bf16 v[0:15], v[174:177], v[178:181], v[0:15]
	ds_read_b128 v[160:163], v94
	ds_read_b128 v[164:167], v95 offset:32768
	ds_read_b128 v[174:177], v94 offset:4096
	ds_read_b128 v[178:181], v95 offset:36864
	s_waitcnt lgkmcnt(2)
	v_mfma_f32_32x32x16_bf16 v[48:63], v[160:163], v[164:167], v[48:63]
	s_waitcnt lgkmcnt(0)
	v_mfma_f32_32x32x16_bf16 v[32:47], v[160:163], v[178:181], v[32:47]
	v_mfma_f32_32x32x16_bf16 v[16:31], v[174:177], v[164:167], v[16:31]
	v_mfma_f32_32x32x16_bf16 v[0:15], v[174:177], v[178:181], v[0:15]
	ds_read_b128 v[160:163], v92
	ds_read_b128 v[164:167], v93 offset:32768
	ds_read_b128 v[174:177], v92 offset:4096
	ds_read_b128 v[178:181], v93 offset:36864
	s_waitcnt lgkmcnt(2)
	v_mfma_f32_32x32x16_bf16 v[48:63], v[160:163], v[164:167], v[48:63]
	s_waitcnt lgkmcnt(0)
	v_mfma_f32_32x32x16_bf16 v[32:47], v[160:163], v[178:181], v[32:47]
	v_mfma_f32_32x32x16_bf16 v[16:31], v[174:177], v[164:167], v[16:31]
	v_mfma_f32_32x32x16_bf16 v[0:15], v[174:177], v[178:181], v[0:15]
	ds_read_b128 v[160:163], v90
	ds_read_b128 v[164:167], v91 offset:32768
	ds_read_b128 v[174:177], v90 offset:4096
	ds_read_b128 v[178:181], v91 offset:36864
	s_waitcnt lgkmcnt(2)
	v_mfma_f32_32x32x16_bf16 v[48:63], v[160:163], v[164:167], v[48:63]
	s_waitcnt lgkmcnt(0)
	v_mfma_f32_32x32x16_bf16 v[32:47], v[160:163], v[178:181], v[32:47]
	v_mfma_f32_32x32x16_bf16 v[16:31], v[174:177], v[164:167], v[16:31]
	v_mfma_f32_32x32x16_bf16 v[0:15], v[174:177], v[178:181], v[0:15]
	ds_read_b128 v[160:163], v88
	ds_read_b128 v[164:167], v89 offset:32768
	ds_read_b128 v[174:177], v88 offset:4096
	ds_read_b128 v[178:181], v89 offset:36864
	s_waitcnt vmcnt(13)
	ds_write_b128 v87, v[104:107] offset:16384
	ds_write_b128 v87, v[96:99] offset:20480
	ds_write_b128 v87, v[100:103] offset:24576
	s_waitcnt vmcnt(11)
	ds_write_b128 v87, v[112:115] offset:28672
	ds_write_b128 v87, v[108:111] offset:49152
	s_waitcnt vmcnt(10)
	ds_write_b128 v87, v[116:119] offset:53248
	s_waitcnt vmcnt(9)
	ds_write_b128 v87, v[120:123] offset:57344
	s_waitcnt vmcnt(8)
	ds_write_b128 v87, v[124:127] offset:61440
	s_waitcnt lgkmcnt(0)
	s_barrier
	global_load_dwordx4 v[96:99], v[70:71], off offset:640
	global_load_dwordx4 v[100:103], v[72:73], off offset:640
	global_load_dwordx4 v[104:107], v[66:67], off offset:640
	global_load_dwordx4 v[108:111], v[68:69], off offset:640
	global_load_dwordx4 v[112:115], v[74:75], off offset:640
	global_load_dwordx4 v[116:119], v[76:77], off offset:640
	global_load_dwordx4 v[120:123], v[78:79], off offset:640
	global_load_dwordx4 v[124:127], v[82:83], off offset:640
	v_mfma_f32_32x32x16_bf16 v[48:63], v[160:163], v[164:167], v[48:63]
	v_mfma_f32_32x32x16_bf16 v[32:47], v[160:163], v[178:181], v[32:47]
	v_mfma_f32_32x32x16_bf16 v[16:31], v[174:177], v[164:167], v[16:31]
	v_mfma_f32_32x32x16_bf16 v[0:15], v[174:177], v[178:181], v[0:15]
	ds_read_b128 v[160:163], v94 offset:16384
	ds_read_b128 v[164:167], v95 offset:49152
	ds_read_b128 v[174:177], v94 offset:20480
	ds_read_b128 v[178:181], v95 offset:53248
	s_waitcnt lgkmcnt(2)
	v_mfma_f32_32x32x16_bf16 v[48:63], v[160:163], v[164:167], v[48:63]
	s_waitcnt lgkmcnt(0)
	v_mfma_f32_32x32x16_bf16 v[32:47], v[160:163], v[178:181], v[32:47]
	v_mfma_f32_32x32x16_bf16 v[16:31], v[174:177], v[164:167], v[16:31]
	v_mfma_f32_32x32x16_bf16 v[0:15], v[174:177], v[178:181], v[0:15]
	ds_read_b128 v[160:163], v92 offset:16384
	ds_read_b128 v[164:167], v93 offset:49152
	ds_read_b128 v[174:177], v92 offset:20480
	ds_read_b128 v[178:181], v93 offset:53248
	s_waitcnt lgkmcnt(2)
	v_mfma_f32_32x32x16_bf16 v[48:63], v[160:163], v[164:167], v[48:63]
	s_waitcnt lgkmcnt(0)
	v_mfma_f32_32x32x16_bf16 v[32:47], v[160:163], v[178:181], v[32:47]
	v_mfma_f32_32x32x16_bf16 v[16:31], v[174:177], v[164:167], v[16:31]
	v_mfma_f32_32x32x16_bf16 v[0:15], v[174:177], v[178:181], v[0:15]
	ds_read_b128 v[160:163], v90 offset:16384
	ds_read_b128 v[164:167], v91 offset:49152
	ds_read_b128 v[174:177], v90 offset:20480
	ds_read_b128 v[178:181], v91 offset:53248
	s_waitcnt lgkmcnt(2)
	v_mfma_f32_32x32x16_bf16 v[48:63], v[160:163], v[164:167], v[48:63]
	s_waitcnt lgkmcnt(0)
	v_mfma_f32_32x32x16_bf16 v[32:47], v[160:163], v[178:181], v[32:47]
	v_mfma_f32_32x32x16_bf16 v[16:31], v[174:177], v[164:167], v[16:31]
	v_mfma_f32_32x32x16_bf16 v[0:15], v[174:177], v[178:181], v[0:15]
	ds_read_b128 v[160:163], v88 offset:16384
	ds_read_b128 v[164:167], v89 offset:49152
	ds_read_b128 v[174:177], v88 offset:20480
	ds_read_b128 v[178:181], v89 offset:53248
	s_waitcnt vmcnt(13)
	ds_write_b128 v87, v[136:139]
	ds_write_b128 v87, v[128:131] offset:4096
	ds_write_b128 v87, v[132:135] offset:8192
	s_waitcnt vmcnt(11)
	ds_write_b128 v87, v[144:147] offset:12288
	ds_write_b128 v87, v[140:143] offset:32768
	s_waitcnt vmcnt(10)
	ds_write_b128 v87, v[148:151] offset:36864
	s_waitcnt vmcnt(9)
	ds_write_b128 v87, v[152:155] offset:40960
	s_waitcnt vmcnt(8)
	ds_write_b128 v87, v[156:159] offset:45056
	s_waitcnt lgkmcnt(0)
	s_barrier
	global_load_dwordx4 v[128:131], v[70:71], off offset:768
	global_load_dwordx4 v[132:135], v[72:73], off offset:768
	global_load_dwordx4 v[136:139], v[66:67], off offset:768
	global_load_dwordx4 v[140:143], v[68:69], off offset:768
	global_load_dwordx4 v[144:147], v[74:75], off offset:768
	global_load_dwordx4 v[148:151], v[76:77], off offset:768
	global_load_dwordx4 v[152:155], v[78:79], off offset:768
	global_load_dwordx4 v[156:159], v[82:83], off offset:768
	v_mfma_f32_32x32x16_bf16 v[48:63], v[160:163], v[164:167], v[48:63]
	v_mfma_f32_32x32x16_bf16 v[32:47], v[160:163], v[178:181], v[32:47]
	v_mfma_f32_32x32x16_bf16 v[16:31], v[174:177], v[164:167], v[16:31]
	v_mfma_f32_32x32x16_bf16 v[0:15], v[174:177], v[178:181], v[0:15]
	ds_read_b128 v[160:163], v94
	ds_read_b128 v[164:167], v95 offset:32768
	ds_read_b128 v[174:177], v94 offset:4096
	ds_read_b128 v[178:181], v95 offset:36864
	s_waitcnt lgkmcnt(2)
	v_mfma_f32_32x32x16_bf16 v[48:63], v[160:163], v[164:167], v[48:63]
	s_waitcnt lgkmcnt(0)
	v_mfma_f32_32x32x16_bf16 v[32:47], v[160:163], v[178:181], v[32:47]
	v_mfma_f32_32x32x16_bf16 v[16:31], v[174:177], v[164:167], v[16:31]
	v_mfma_f32_32x32x16_bf16 v[0:15], v[174:177], v[178:181], v[0:15]
	ds_read_b128 v[160:163], v92
	ds_read_b128 v[164:167], v93 offset:32768
	ds_read_b128 v[174:177], v92 offset:4096
	ds_read_b128 v[178:181], v93 offset:36864
	s_waitcnt lgkmcnt(2)
	v_mfma_f32_32x32x16_bf16 v[48:63], v[160:163], v[164:167], v[48:63]
	s_waitcnt lgkmcnt(0)
	v_mfma_f32_32x32x16_bf16 v[32:47], v[160:163], v[178:181], v[32:47]
	v_mfma_f32_32x32x16_bf16 v[16:31], v[174:177], v[164:167], v[16:31]
	v_mfma_f32_32x32x16_bf16 v[0:15], v[174:177], v[178:181], v[0:15]
	ds_read_b128 v[160:163], v90
	ds_read_b128 v[164:167], v91 offset:32768
	ds_read_b128 v[174:177], v90 offset:4096
	ds_read_b128 v[178:181], v91 offset:36864
	s_waitcnt lgkmcnt(2)
	v_mfma_f32_32x32x16_bf16 v[48:63], v[160:163], v[164:167], v[48:63]
	s_waitcnt lgkmcnt(0)
	v_mfma_f32_32x32x16_bf16 v[32:47], v[160:163], v[178:181], v[32:47]
	v_mfma_f32_32x32x16_bf16 v[16:31], v[174:177], v[164:167], v[16:31]
	v_mfma_f32_32x32x16_bf16 v[0:15], v[174:177], v[178:181], v[0:15]
	ds_read_b128 v[160:163], v88
	ds_read_b128 v[164:167], v89 offset:32768
	ds_read_b128 v[174:177], v88 offset:4096
	ds_read_b128 v[178:181], v89 offset:36864
	s_waitcnt vmcnt(13)
	ds_write_b128 v87, v[104:107] offset:16384
	ds_write_b128 v87, v[96:99] offset:20480
	ds_write_b128 v87, v[100:103] offset:24576
	s_waitcnt vmcnt(11)
	ds_write_b128 v87, v[112:115] offset:28672
	ds_write_b128 v87, v[108:111] offset:49152
	s_waitcnt vmcnt(10)
	ds_write_b128 v87, v[116:119] offset:53248
	s_waitcnt vmcnt(9)
	ds_write_b128 v87, v[120:123] offset:57344
	s_waitcnt vmcnt(8)
	ds_write_b128 v87, v[124:127] offset:61440
	s_waitcnt lgkmcnt(0)
	s_barrier
	global_load_dwordx4 v[96:99], v[70:71], off offset:896
	global_load_dwordx4 v[100:103], v[72:73], off offset:896
	global_load_dwordx4 v[104:107], v[66:67], off offset:896
	global_load_dwordx4 v[108:111], v[68:69], off offset:896
	global_load_dwordx4 v[112:115], v[74:75], off offset:896
	global_load_dwordx4 v[116:119], v[76:77], off offset:896
	global_load_dwordx4 v[120:123], v[78:79], off offset:896
	global_load_dwordx4 v[124:127], v[82:83], off offset:896
	v_mfma_f32_32x32x16_bf16 v[48:63], v[160:163], v[164:167], v[48:63]
	v_mfma_f32_32x32x16_bf16 v[32:47], v[160:163], v[178:181], v[32:47]
	v_mfma_f32_32x32x16_bf16 v[16:31], v[174:177], v[164:167], v[16:31]
	v_mfma_f32_32x32x16_bf16 v[0:15], v[174:177], v[178:181], v[0:15]
	ds_read_b128 v[160:163], v94 offset:16384
	ds_read_b128 v[164:167], v95 offset:49152
	ds_read_b128 v[174:177], v94 offset:20480
	ds_read_b128 v[178:181], v95 offset:53248
	s_waitcnt lgkmcnt(2)
	v_mfma_f32_32x32x16_bf16 v[48:63], v[160:163], v[164:167], v[48:63]
	s_waitcnt lgkmcnt(0)
	v_mfma_f32_32x32x16_bf16 v[32:47], v[160:163], v[178:181], v[32:47]
	v_mfma_f32_32x32x16_bf16 v[16:31], v[174:177], v[164:167], v[16:31]
	v_mfma_f32_32x32x16_bf16 v[0:15], v[174:177], v[178:181], v[0:15]
	ds_read_b128 v[160:163], v92 offset:16384
	ds_read_b128 v[164:167], v93 offset:49152
	ds_read_b128 v[174:177], v92 offset:20480
	ds_read_b128 v[178:181], v93 offset:53248
	s_waitcnt lgkmcnt(2)
	v_mfma_f32_32x32x16_bf16 v[48:63], v[160:163], v[164:167], v[48:63]
	s_waitcnt lgkmcnt(0)
	v_mfma_f32_32x32x16_bf16 v[32:47], v[160:163], v[178:181], v[32:47]
	v_mfma_f32_32x32x16_bf16 v[16:31], v[174:177], v[164:167], v[16:31]
	v_mfma_f32_32x32x16_bf16 v[0:15], v[174:177], v[178:181], v[0:15]
	ds_read_b128 v[160:163], v90 offset:16384
	ds_read_b128 v[164:167], v91 offset:49152
	ds_read_b128 v[174:177], v90 offset:20480
	ds_read_b128 v[178:181], v91 offset:53248
	s_waitcnt lgkmcnt(2)
	v_mfma_f32_32x32x16_bf16 v[48:63], v[160:163], v[164:167], v[48:63]
	s_waitcnt lgkmcnt(0)
	v_mfma_f32_32x32x16_bf16 v[32:47], v[160:163], v[178:181], v[32:47]
	v_mfma_f32_32x32x16_bf16 v[16:31], v[174:177], v[164:167], v[16:31]
	v_mfma_f32_32x32x16_bf16 v[0:15], v[174:177], v[178:181], v[0:15]
	ds_read_b128 v[160:163], v88 offset:16384
	ds_read_b128 v[164:167], v89 offset:49152
	ds_read_b128 v[174:177], v88 offset:20480
	ds_read_b128 v[178:181], v89 offset:53248
	s_waitcnt vmcnt(13)
	ds_write_b128 v87, v[136:139]
	ds_write_b128 v87, v[128:131] offset:4096
	ds_write_b128 v87, v[132:135] offset:8192
	s_waitcnt vmcnt(11)
	ds_write_b128 v87, v[144:147] offset:12288
	ds_write_b128 v87, v[140:143] offset:32768
	s_waitcnt vmcnt(10)
	ds_write_b128 v87, v[148:151] offset:36864
	s_waitcnt vmcnt(9)
	ds_write_b128 v87, v[152:155] offset:40960
	s_waitcnt vmcnt(8)
	ds_write_b128 v87, v[156:159] offset:45056
	s_waitcnt lgkmcnt(0)
	s_barrier
	global_load_dwordx4 v[128:131], v[70:71], off offset:1024
	global_load_dwordx4 v[132:135], v[72:73], off offset:1024
	global_load_dwordx4 v[136:139], v[66:67], off offset:1024
	global_load_dwordx4 v[140:143], v[68:69], off offset:1024
	global_load_dwordx4 v[144:147], v[74:75], off offset:1024
	global_load_dwordx4 v[148:151], v[76:77], off offset:1024
	global_load_dwordx4 v[152:155], v[78:79], off offset:1024
	global_load_dwordx4 v[156:159], v[82:83], off offset:1024
	v_mfma_f32_32x32x16_bf16 v[48:63], v[160:163], v[164:167], v[48:63]
	v_mfma_f32_32x32x16_bf16 v[32:47], v[160:163], v[178:181], v[32:47]
	v_mfma_f32_32x32x16_bf16 v[16:31], v[174:177], v[164:167], v[16:31]
	v_mfma_f32_32x32x16_bf16 v[0:15], v[174:177], v[178:181], v[0:15]
	ds_read_b128 v[160:163], v94
	ds_read_b128 v[164:167], v95 offset:32768
	ds_read_b128 v[174:177], v94 offset:4096
	ds_read_b128 v[178:181], v95 offset:36864
	s_waitcnt lgkmcnt(2)
	v_mfma_f32_32x32x16_bf16 v[48:63], v[160:163], v[164:167], v[48:63]
	s_waitcnt lgkmcnt(0)
	v_mfma_f32_32x32x16_bf16 v[32:47], v[160:163], v[178:181], v[32:47]
	v_mfma_f32_32x32x16_bf16 v[16:31], v[174:177], v[164:167], v[16:31]
	v_mfma_f32_32x32x16_bf16 v[0:15], v[174:177], v[178:181], v[0:15]
	ds_read_b128 v[160:163], v92
	ds_read_b128 v[164:167], v93 offset:32768
	ds_read_b128 v[174:177], v92 offset:4096
	ds_read_b128 v[178:181], v93 offset:36864
	s_waitcnt lgkmcnt(2)
	v_mfma_f32_32x32x16_bf16 v[48:63], v[160:163], v[164:167], v[48:63]
	s_waitcnt lgkmcnt(0)
	v_mfma_f32_32x32x16_bf16 v[32:47], v[160:163], v[178:181], v[32:47]
	v_mfma_f32_32x32x16_bf16 v[16:31], v[174:177], v[164:167], v[16:31]
	v_mfma_f32_32x32x16_bf16 v[0:15], v[174:177], v[178:181], v[0:15]
	ds_read_b128 v[160:163], v90
	ds_read_b128 v[164:167], v91 offset:32768
	ds_read_b128 v[174:177], v90 offset:4096
	ds_read_b128 v[178:181], v91 offset:36864
	s_waitcnt lgkmcnt(2)
	v_mfma_f32_32x32x16_bf16 v[48:63], v[160:163], v[164:167], v[48:63]
	s_waitcnt lgkmcnt(0)
	v_mfma_f32_32x32x16_bf16 v[32:47], v[160:163], v[178:181], v[32:47]
	v_mfma_f32_32x32x16_bf16 v[16:31], v[174:177], v[164:167], v[16:31]
	v_mfma_f32_32x32x16_bf16 v[0:15], v[174:177], v[178:181], v[0:15]
	ds_read_b128 v[160:163], v88
	ds_read_b128 v[164:167], v89 offset:32768
	ds_read_b128 v[174:177], v88 offset:4096
	ds_read_b128 v[178:181], v89 offset:36864
	s_waitcnt vmcnt(13)
	ds_write_b128 v87, v[104:107] offset:16384
	ds_write_b128 v87, v[96:99] offset:20480
	ds_write_b128 v87, v[100:103] offset:24576
	s_waitcnt vmcnt(11)
	ds_write_b128 v87, v[112:115] offset:28672
	ds_write_b128 v87, v[108:111] offset:49152
	s_waitcnt vmcnt(10)
	ds_write_b128 v87, v[116:119] offset:53248
	s_waitcnt vmcnt(9)
	ds_write_b128 v87, v[120:123] offset:57344
	s_waitcnt vmcnt(8)
	ds_write_b128 v87, v[124:127] offset:61440
	s_waitcnt lgkmcnt(0)
	s_barrier
	global_load_dwordx4 v[96:99], v[70:71], off offset:1152
	global_load_dwordx4 v[100:103], v[72:73], off offset:1152
	global_load_dwordx4 v[104:107], v[66:67], off offset:1152
	global_load_dwordx4 v[108:111], v[68:69], off offset:1152
	global_load_dwordx4 v[112:115], v[74:75], off offset:1152
	global_load_dwordx4 v[116:119], v[76:77], off offset:1152
	global_load_dwordx4 v[120:123], v[78:79], off offset:1152
	global_load_dwordx4 v[124:127], v[82:83], off offset:1152
	v_mfma_f32_32x32x16_bf16 v[48:63], v[160:163], v[164:167], v[48:63]
	v_mfma_f32_32x32x16_bf16 v[32:47], v[160:163], v[178:181], v[32:47]
	v_mfma_f32_32x32x16_bf16 v[16:31], v[174:177], v[164:167], v[16:31]
	v_mfma_f32_32x32x16_bf16 v[0:15], v[174:177], v[178:181], v[0:15]
	ds_read_b128 v[160:163], v94 offset:16384
	ds_read_b128 v[164:167], v95 offset:49152
	ds_read_b128 v[174:177], v94 offset:20480
	ds_read_b128 v[178:181], v95 offset:53248
	s_waitcnt lgkmcnt(2)
	v_mfma_f32_32x32x16_bf16 v[48:63], v[160:163], v[164:167], v[48:63]
	s_waitcnt lgkmcnt(0)
	v_mfma_f32_32x32x16_bf16 v[32:47], v[160:163], v[178:181], v[32:47]
	v_mfma_f32_32x32x16_bf16 v[16:31], v[174:177], v[164:167], v[16:31]
	v_mfma_f32_32x32x16_bf16 v[0:15], v[174:177], v[178:181], v[0:15]
	ds_read_b128 v[160:163], v92 offset:16384
	ds_read_b128 v[164:167], v93 offset:49152
	ds_read_b128 v[174:177], v92 offset:20480
	ds_read_b128 v[178:181], v93 offset:53248
	s_waitcnt lgkmcnt(2)
	v_mfma_f32_32x32x16_bf16 v[48:63], v[160:163], v[164:167], v[48:63]
	s_waitcnt lgkmcnt(0)
	v_mfma_f32_32x32x16_bf16 v[32:47], v[160:163], v[178:181], v[32:47]
	v_mfma_f32_32x32x16_bf16 v[16:31], v[174:177], v[164:167], v[16:31]
	v_mfma_f32_32x32x16_bf16 v[0:15], v[174:177], v[178:181], v[0:15]
	ds_read_b128 v[160:163], v90 offset:16384
	ds_read_b128 v[164:167], v91 offset:49152
	ds_read_b128 v[174:177], v90 offset:20480
	ds_read_b128 v[178:181], v91 offset:53248
	s_waitcnt lgkmcnt(2)
	v_mfma_f32_32x32x16_bf16 v[48:63], v[160:163], v[164:167], v[48:63]
	s_waitcnt lgkmcnt(0)
	v_mfma_f32_32x32x16_bf16 v[32:47], v[160:163], v[178:181], v[32:47]
	v_mfma_f32_32x32x16_bf16 v[16:31], v[174:177], v[164:167], v[16:31]
	v_mfma_f32_32x32x16_bf16 v[0:15], v[174:177], v[178:181], v[0:15]
	ds_read_b128 v[160:163], v88 offset:16384
	ds_read_b128 v[164:167], v89 offset:49152
	ds_read_b128 v[174:177], v88 offset:20480
	ds_read_b128 v[178:181], v89 offset:53248
	s_waitcnt vmcnt(13)
	ds_write_b128 v87, v[136:139]
	ds_write_b128 v87, v[128:131] offset:4096
	ds_write_b128 v87, v[132:135] offset:8192
	s_waitcnt vmcnt(11)
	ds_write_b128 v87, v[144:147] offset:12288
	ds_write_b128 v87, v[140:143] offset:32768
	s_waitcnt vmcnt(10)
	ds_write_b128 v87, v[148:151] offset:36864
	s_waitcnt vmcnt(9)
	ds_write_b128 v87, v[152:155] offset:40960
	s_waitcnt vmcnt(8)
	ds_write_b128 v87, v[156:159] offset:45056
	s_waitcnt lgkmcnt(0)
	s_barrier
	global_load_dwordx4 v[128:131], v[70:71], off offset:1280
	global_load_dwordx4 v[132:135], v[72:73], off offset:1280
	global_load_dwordx4 v[136:139], v[66:67], off offset:1280
	global_load_dwordx4 v[140:143], v[68:69], off offset:1280
	global_load_dwordx4 v[144:147], v[74:75], off offset:1280
	global_load_dwordx4 v[148:151], v[76:77], off offset:1280
	global_load_dwordx4 v[152:155], v[78:79], off offset:1280
	global_load_dwordx4 v[156:159], v[82:83], off offset:1280
	v_mfma_f32_32x32x16_bf16 v[48:63], v[160:163], v[164:167], v[48:63]
	v_mfma_f32_32x32x16_bf16 v[32:47], v[160:163], v[178:181], v[32:47]
	v_mfma_f32_32x32x16_bf16 v[16:31], v[174:177], v[164:167], v[16:31]
	v_mfma_f32_32x32x16_bf16 v[0:15], v[174:177], v[178:181], v[0:15]
	ds_read_b128 v[160:163], v94
	ds_read_b128 v[164:167], v95 offset:32768
	ds_read_b128 v[174:177], v94 offset:4096
	ds_read_b128 v[178:181], v95 offset:36864
	s_waitcnt lgkmcnt(2)
	v_mfma_f32_32x32x16_bf16 v[48:63], v[160:163], v[164:167], v[48:63]
	s_waitcnt lgkmcnt(0)
	v_mfma_f32_32x32x16_bf16 v[32:47], v[160:163], v[178:181], v[32:47]
	v_mfma_f32_32x32x16_bf16 v[16:31], v[174:177], v[164:167], v[16:31]
	v_mfma_f32_32x32x16_bf16 v[0:15], v[174:177], v[178:181], v[0:15]
	ds_read_b128 v[160:163], v92
	ds_read_b128 v[164:167], v93 offset:32768
	ds_read_b128 v[174:177], v92 offset:4096
	ds_read_b128 v[178:181], v93 offset:36864
	s_waitcnt lgkmcnt(2)
	v_mfma_f32_32x32x16_bf16 v[48:63], v[160:163], v[164:167], v[48:63]
	s_waitcnt lgkmcnt(0)
	v_mfma_f32_32x32x16_bf16 v[32:47], v[160:163], v[178:181], v[32:47]
	v_mfma_f32_32x32x16_bf16 v[16:31], v[174:177], v[164:167], v[16:31]
	v_mfma_f32_32x32x16_bf16 v[0:15], v[174:177], v[178:181], v[0:15]
	ds_read_b128 v[160:163], v90
	ds_read_b128 v[164:167], v91 offset:32768
	ds_read_b128 v[174:177], v90 offset:4096
	ds_read_b128 v[178:181], v91 offset:36864
	s_waitcnt lgkmcnt(2)
	v_mfma_f32_32x32x16_bf16 v[48:63], v[160:163], v[164:167], v[48:63]
	s_waitcnt lgkmcnt(0)
	v_mfma_f32_32x32x16_bf16 v[32:47], v[160:163], v[178:181], v[32:47]
	v_mfma_f32_32x32x16_bf16 v[16:31], v[174:177], v[164:167], v[16:31]
	v_mfma_f32_32x32x16_bf16 v[0:15], v[174:177], v[178:181], v[0:15]
	ds_read_b128 v[160:163], v88
	ds_read_b128 v[164:167], v89 offset:32768
	ds_read_b128 v[174:177], v88 offset:4096
	ds_read_b128 v[178:181], v89 offset:36864
	s_waitcnt vmcnt(13)
	ds_write_b128 v87, v[104:107] offset:16384
	ds_write_b128 v87, v[96:99] offset:20480
	ds_write_b128 v87, v[100:103] offset:24576
	s_waitcnt vmcnt(11)
	ds_write_b128 v87, v[112:115] offset:28672
	ds_write_b128 v87, v[108:111] offset:49152
	s_waitcnt vmcnt(10)
	ds_write_b128 v87, v[116:119] offset:53248
	s_waitcnt vmcnt(9)
	ds_write_b128 v87, v[120:123] offset:57344
	s_waitcnt vmcnt(8)
	ds_write_b128 v87, v[124:127] offset:61440
	s_waitcnt lgkmcnt(0)
	s_barrier
	global_load_dwordx4 v[96:99], v[70:71], off offset:1408
	global_load_dwordx4 v[100:103], v[72:73], off offset:1408
	global_load_dwordx4 v[104:107], v[66:67], off offset:1408
	global_load_dwordx4 v[108:111], v[68:69], off offset:1408
	global_load_dwordx4 v[112:115], v[74:75], off offset:1408
	global_load_dwordx4 v[116:119], v[76:77], off offset:1408
	global_load_dwordx4 v[120:123], v[78:79], off offset:1408
	global_load_dwordx4 v[124:127], v[82:83], off offset:1408
	v_mfma_f32_32x32x16_bf16 v[48:63], v[160:163], v[164:167], v[48:63]
	v_mfma_f32_32x32x16_bf16 v[32:47], v[160:163], v[178:181], v[32:47]
	v_mfma_f32_32x32x16_bf16 v[16:31], v[174:177], v[164:167], v[16:31]
	v_mfma_f32_32x32x16_bf16 v[0:15], v[174:177], v[178:181], v[0:15]
	ds_read_b128 v[160:163], v94 offset:16384
	ds_read_b128 v[164:167], v95 offset:49152
	ds_read_b128 v[174:177], v94 offset:20480
	ds_read_b128 v[178:181], v95 offset:53248
	s_waitcnt lgkmcnt(2)
	v_mfma_f32_32x32x16_bf16 v[48:63], v[160:163], v[164:167], v[48:63]
	s_waitcnt lgkmcnt(0)
	v_mfma_f32_32x32x16_bf16 v[32:47], v[160:163], v[178:181], v[32:47]
	v_mfma_f32_32x32x16_bf16 v[16:31], v[174:177], v[164:167], v[16:31]
	v_mfma_f32_32x32x16_bf16 v[0:15], v[174:177], v[178:181], v[0:15]
	ds_read_b128 v[160:163], v92 offset:16384
	ds_read_b128 v[164:167], v93 offset:49152
	ds_read_b128 v[174:177], v92 offset:20480
	ds_read_b128 v[178:181], v93 offset:53248
	s_waitcnt lgkmcnt(2)
	v_mfma_f32_32x32x16_bf16 v[48:63], v[160:163], v[164:167], v[48:63]
	s_waitcnt lgkmcnt(0)
	v_mfma_f32_32x32x16_bf16 v[32:47], v[160:163], v[178:181], v[32:47]
	v_mfma_f32_32x32x16_bf16 v[16:31], v[174:177], v[164:167], v[16:31]
	v_mfma_f32_32x32x16_bf16 v[0:15], v[174:177], v[178:181], v[0:15]
	ds_read_b128 v[160:163], v90 offset:16384
	ds_read_b128 v[164:167], v91 offset:49152
	ds_read_b128 v[174:177], v90 offset:20480
	ds_read_b128 v[178:181], v91 offset:53248
	s_waitcnt lgkmcnt(2)
	v_mfma_f32_32x32x16_bf16 v[48:63], v[160:163], v[164:167], v[48:63]
	s_waitcnt lgkmcnt(0)
	v_mfma_f32_32x32x16_bf16 v[32:47], v[160:163], v[178:181], v[32:47]
	v_mfma_f32_32x32x16_bf16 v[16:31], v[174:177], v[164:167], v[16:31]
	v_mfma_f32_32x32x16_bf16 v[0:15], v[174:177], v[178:181], v[0:15]
	ds_read_b128 v[160:163], v88 offset:16384
	ds_read_b128 v[164:167], v89 offset:49152
	ds_read_b128 v[174:177], v88 offset:20480
	ds_read_b128 v[178:181], v89 offset:53248
	s_waitcnt vmcnt(13)
	ds_write_b128 v87, v[136:139]
	ds_write_b128 v87, v[128:131] offset:4096
	ds_write_b128 v87, v[132:135] offset:8192
	s_waitcnt vmcnt(11)
	ds_write_b128 v87, v[144:147] offset:12288
	ds_write_b128 v87, v[140:143] offset:32768
	s_waitcnt vmcnt(10)
	ds_write_b128 v87, v[148:151] offset:36864
	s_waitcnt vmcnt(9)
	ds_write_b128 v87, v[152:155] offset:40960
	s_waitcnt vmcnt(8)
	ds_write_b128 v87, v[156:159] offset:45056
	s_waitcnt lgkmcnt(0)
	s_barrier
	global_load_dwordx4 v[128:131], v[70:71], off offset:1536
	global_load_dwordx4 v[132:135], v[72:73], off offset:1536
	global_load_dwordx4 v[136:139], v[66:67], off offset:1536
	global_load_dwordx4 v[140:143], v[68:69], off offset:1536
	global_load_dwordx4 v[144:147], v[74:75], off offset:1536
	global_load_dwordx4 v[148:151], v[76:77], off offset:1536
	global_load_dwordx4 v[152:155], v[78:79], off offset:1536
	global_load_dwordx4 v[156:159], v[82:83], off offset:1536
	v_mfma_f32_32x32x16_bf16 v[48:63], v[160:163], v[164:167], v[48:63]
	v_mfma_f32_32x32x16_bf16 v[32:47], v[160:163], v[178:181], v[32:47]
	v_mfma_f32_32x32x16_bf16 v[16:31], v[174:177], v[164:167], v[16:31]
	v_mfma_f32_32x32x16_bf16 v[0:15], v[174:177], v[178:181], v[0:15]
	ds_read_b128 v[160:163], v94
	ds_read_b128 v[164:167], v95 offset:32768
	ds_read_b128 v[174:177], v94 offset:4096
	ds_read_b128 v[178:181], v95 offset:36864
	s_waitcnt lgkmcnt(2)
	v_mfma_f32_32x32x16_bf16 v[48:63], v[160:163], v[164:167], v[48:63]
	s_waitcnt lgkmcnt(0)
	v_mfma_f32_32x32x16_bf16 v[32:47], v[160:163], v[178:181], v[32:47]
	v_mfma_f32_32x32x16_bf16 v[16:31], v[174:177], v[164:167], v[16:31]
	v_mfma_f32_32x32x16_bf16 v[0:15], v[174:177], v[178:181], v[0:15]
	ds_read_b128 v[160:163], v92
	ds_read_b128 v[164:167], v93 offset:32768
	ds_read_b128 v[174:177], v92 offset:4096
	ds_read_b128 v[178:181], v93 offset:36864
	s_waitcnt lgkmcnt(2)
	v_mfma_f32_32x32x16_bf16 v[48:63], v[160:163], v[164:167], v[48:63]
	s_waitcnt lgkmcnt(0)
	v_mfma_f32_32x32x16_bf16 v[32:47], v[160:163], v[178:181], v[32:47]
	v_mfma_f32_32x32x16_bf16 v[16:31], v[174:177], v[164:167], v[16:31]
	v_mfma_f32_32x32x16_bf16 v[0:15], v[174:177], v[178:181], v[0:15]
	ds_read_b128 v[160:163], v90
	ds_read_b128 v[164:167], v91 offset:32768
	ds_read_b128 v[174:177], v90 offset:4096
	ds_read_b128 v[178:181], v91 offset:36864
	s_waitcnt lgkmcnt(2)
	v_mfma_f32_32x32x16_bf16 v[48:63], v[160:163], v[164:167], v[48:63]
	s_waitcnt lgkmcnt(0)
	v_mfma_f32_32x32x16_bf16 v[32:47], v[160:163], v[178:181], v[32:47]
	v_mfma_f32_32x32x16_bf16 v[16:31], v[174:177], v[164:167], v[16:31]
	v_mfma_f32_32x32x16_bf16 v[0:15], v[174:177], v[178:181], v[0:15]
	ds_read_b128 v[160:163], v88
	ds_read_b128 v[164:167], v89 offset:32768
	ds_read_b128 v[174:177], v88 offset:4096
	ds_read_b128 v[178:181], v89 offset:36864
	s_waitcnt vmcnt(13)
	ds_write_b128 v87, v[104:107] offset:16384
	ds_write_b128 v87, v[96:99] offset:20480
	ds_write_b128 v87, v[100:103] offset:24576
	s_waitcnt vmcnt(11)
	ds_write_b128 v87, v[112:115] offset:28672
	ds_write_b128 v87, v[108:111] offset:49152
	s_waitcnt vmcnt(10)
	ds_write_b128 v87, v[116:119] offset:53248
	s_waitcnt vmcnt(9)
	ds_write_b128 v87, v[120:123] offset:57344
	s_waitcnt vmcnt(8)
	ds_write_b128 v87, v[124:127] offset:61440
	s_waitcnt lgkmcnt(0)
	s_barrier
	global_load_dwordx4 v[96:99], v[70:71], off offset:1664
	global_load_dwordx4 v[100:103], v[72:73], off offset:1664
	global_load_dwordx4 v[104:107], v[66:67], off offset:1664
	global_load_dwordx4 v[108:111], v[68:69], off offset:1664
	global_load_dwordx4 v[112:115], v[74:75], off offset:1664
	global_load_dwordx4 v[116:119], v[76:77], off offset:1664
	global_load_dwordx4 v[120:123], v[78:79], off offset:1664
	global_load_dwordx4 v[124:127], v[82:83], off offset:1664
	v_mfma_f32_32x32x16_bf16 v[48:63], v[160:163], v[164:167], v[48:63]
	v_mfma_f32_32x32x16_bf16 v[32:47], v[160:163], v[178:181], v[32:47]
	v_mfma_f32_32x32x16_bf16 v[16:31], v[174:177], v[164:167], v[16:31]
	v_mfma_f32_32x32x16_bf16 v[0:15], v[174:177], v[178:181], v[0:15]
	ds_read_b128 v[160:163], v94 offset:16384
	ds_read_b128 v[164:167], v95 offset:49152
	ds_read_b128 v[174:177], v94 offset:20480
	ds_read_b128 v[178:181], v95 offset:53248
	s_waitcnt lgkmcnt(2)
	v_mfma_f32_32x32x16_bf16 v[48:63], v[160:163], v[164:167], v[48:63]
	s_waitcnt lgkmcnt(0)
	v_mfma_f32_32x32x16_bf16 v[32:47], v[160:163], v[178:181], v[32:47]
	v_mfma_f32_32x32x16_bf16 v[16:31], v[174:177], v[164:167], v[16:31]
	v_mfma_f32_32x32x16_bf16 v[0:15], v[174:177], v[178:181], v[0:15]
	ds_read_b128 v[160:163], v92 offset:16384
	ds_read_b128 v[164:167], v93 offset:49152
	ds_read_b128 v[174:177], v92 offset:20480
	ds_read_b128 v[178:181], v93 offset:53248
	s_waitcnt lgkmcnt(2)
	v_mfma_f32_32x32x16_bf16 v[48:63], v[160:163], v[164:167], v[48:63]
	s_waitcnt lgkmcnt(0)
	v_mfma_f32_32x32x16_bf16 v[32:47], v[160:163], v[178:181], v[32:47]
	v_mfma_f32_32x32x16_bf16 v[16:31], v[174:177], v[164:167], v[16:31]
	v_mfma_f32_32x32x16_bf16 v[0:15], v[174:177], v[178:181], v[0:15]
	ds_read_b128 v[160:163], v90 offset:16384
	ds_read_b128 v[164:167], v91 offset:49152
	ds_read_b128 v[174:177], v90 offset:20480
	ds_read_b128 v[178:181], v91 offset:53248
	s_waitcnt lgkmcnt(2)
	v_mfma_f32_32x32x16_bf16 v[48:63], v[160:163], v[164:167], v[48:63]
	s_waitcnt lgkmcnt(0)
	v_mfma_f32_32x32x16_bf16 v[32:47], v[160:163], v[178:181], v[32:47]
	v_mfma_f32_32x32x16_bf16 v[16:31], v[174:177], v[164:167], v[16:31]
	v_mfma_f32_32x32x16_bf16 v[0:15], v[174:177], v[178:181], v[0:15]
	ds_read_b128 v[160:163], v88 offset:16384
	ds_read_b128 v[164:167], v89 offset:49152
	ds_read_b128 v[174:177], v88 offset:20480
	ds_read_b128 v[178:181], v89 offset:53248
	s_waitcnt vmcnt(13)
	ds_write_b128 v87, v[136:139]
	ds_write_b128 v87, v[128:131] offset:4096
	ds_write_b128 v87, v[132:135] offset:8192
	s_waitcnt vmcnt(11)
	ds_write_b128 v87, v[144:147] offset:12288
	ds_write_b128 v87, v[140:143] offset:32768
	s_waitcnt vmcnt(10)
	ds_write_b128 v87, v[148:151] offset:36864
	s_waitcnt vmcnt(9)
	ds_write_b128 v87, v[152:155] offset:40960
	s_waitcnt vmcnt(8)
	ds_write_b128 v87, v[156:159] offset:45056
	s_waitcnt lgkmcnt(0)
	s_barrier
	global_load_dwordx4 v[128:131], v[70:71], off offset:1792
	global_load_dwordx4 v[132:135], v[72:73], off offset:1792
	global_load_dwordx4 v[136:139], v[66:67], off offset:1792
	global_load_dwordx4 v[140:143], v[68:69], off offset:1792
	global_load_dwordx4 v[144:147], v[74:75], off offset:1792
	global_load_dwordx4 v[148:151], v[76:77], off offset:1792
	global_load_dwordx4 v[152:155], v[78:79], off offset:1792
	global_load_dwordx4 v[156:159], v[82:83], off offset:1792
	v_mfma_f32_32x32x16_bf16 v[48:63], v[160:163], v[164:167], v[48:63]
	v_mfma_f32_32x32x16_bf16 v[32:47], v[160:163], v[178:181], v[32:47]
	v_mfma_f32_32x32x16_bf16 v[16:31], v[174:177], v[164:167], v[16:31]
	v_mfma_f32_32x32x16_bf16 v[0:15], v[174:177], v[178:181], v[0:15]
	ds_read_b128 v[160:163], v94
	ds_read_b128 v[164:167], v95 offset:32768
	ds_read_b128 v[174:177], v94 offset:4096
	ds_read_b128 v[178:181], v95 offset:36864
	s_waitcnt lgkmcnt(2)
	v_mfma_f32_32x32x16_bf16 v[48:63], v[160:163], v[164:167], v[48:63]
	s_waitcnt lgkmcnt(0)
	v_mfma_f32_32x32x16_bf16 v[32:47], v[160:163], v[178:181], v[32:47]
	v_mfma_f32_32x32x16_bf16 v[16:31], v[174:177], v[164:167], v[16:31]
	v_mfma_f32_32x32x16_bf16 v[0:15], v[174:177], v[178:181], v[0:15]
	ds_read_b128 v[160:163], v92
	ds_read_b128 v[164:167], v93 offset:32768
	ds_read_b128 v[174:177], v92 offset:4096
	ds_read_b128 v[178:181], v93 offset:36864
	s_waitcnt lgkmcnt(2)
	v_mfma_f32_32x32x16_bf16 v[48:63], v[160:163], v[164:167], v[48:63]
	s_waitcnt lgkmcnt(0)
	v_mfma_f32_32x32x16_bf16 v[32:47], v[160:163], v[178:181], v[32:47]
	v_mfma_f32_32x32x16_bf16 v[16:31], v[174:177], v[164:167], v[16:31]
	v_mfma_f32_32x32x16_bf16 v[0:15], v[174:177], v[178:181], v[0:15]
	ds_read_b128 v[160:163], v90
	ds_read_b128 v[164:167], v91 offset:32768
	ds_read_b128 v[174:177], v90 offset:4096
	ds_read_b128 v[178:181], v91 offset:36864
	s_waitcnt lgkmcnt(2)
	v_mfma_f32_32x32x16_bf16 v[48:63], v[160:163], v[164:167], v[48:63]
	s_waitcnt lgkmcnt(0)
	v_mfma_f32_32x32x16_bf16 v[32:47], v[160:163], v[178:181], v[32:47]
	v_mfma_f32_32x32x16_bf16 v[16:31], v[174:177], v[164:167], v[16:31]
	v_mfma_f32_32x32x16_bf16 v[0:15], v[174:177], v[178:181], v[0:15]
	ds_read_b128 v[160:163], v88
	ds_read_b128 v[164:167], v89 offset:32768
	ds_read_b128 v[174:177], v88 offset:4096
	ds_read_b128 v[178:181], v89 offset:36864
	s_waitcnt vmcnt(13)
	ds_write_b128 v87, v[104:107] offset:16384
	ds_write_b128 v87, v[96:99] offset:20480
	ds_write_b128 v87, v[100:103] offset:24576
	s_waitcnt vmcnt(11)
	ds_write_b128 v87, v[112:115] offset:28672
	ds_write_b128 v87, v[108:111] offset:49152
	s_waitcnt vmcnt(10)
	ds_write_b128 v87, v[116:119] offset:53248
	s_waitcnt vmcnt(9)
	ds_write_b128 v87, v[120:123] offset:57344
	s_waitcnt vmcnt(8)
	ds_write_b128 v87, v[124:127] offset:61440
	s_waitcnt lgkmcnt(0)
	s_barrier
	global_load_dwordx4 v[96:99], v[70:71], off offset:1920
	s_nop 0
	global_load_dwordx4 v[70:73], v[72:73], off offset:1920
	s_nop 0
	global_load_dwordx4 v[100:103], v[66:67], off offset:1920
	s_nop 0
	global_load_dwordx4 v[66:69], v[68:69], off offset:1920
	s_nop 0
	global_load_dwordx4 v[104:107], v[74:75], off offset:1920
	s_nop 0
	global_load_dwordx4 v[74:77], v[76:77], off offset:1920
	s_nop 0
	global_load_dwordx4 v[108:111], v[78:79], off offset:1920
	global_load_dwordx4 v[112:115], v[82:83], off offset:1920
	v_mfma_f32_32x32x16_bf16 v[48:63], v[160:163], v[164:167], v[48:63]
	v_mfma_f32_32x32x16_bf16 v[32:47], v[160:163], v[178:181], v[32:47]
	v_mfma_f32_32x32x16_bf16 v[16:31], v[174:177], v[164:167], v[16:31]
	v_mfma_f32_32x32x16_bf16 v[0:15], v[174:177], v[178:181], v[0:15]
	ds_read_b128 v[116:119], v94 offset:16384
	ds_read_b128 v[120:123], v95 offset:49152
	ds_read_b128 v[124:127], v95 offset:53248
	s_waitcnt lgkmcnt(1)
	v_mfma_f32_32x32x16_bf16 v[48:63], v[116:119], v[120:123], v[48:63]
	s_waitcnt lgkmcnt(0)
	v_mfma_f32_32x32x16_bf16 v[32:47], v[116:119], v[124:127], v[32:47]
	ds_read_b128 v[116:119], v94 offset:20480
	s_waitcnt lgkmcnt(0)
	v_mfma_f32_32x32x16_bf16 v[16:31], v[116:119], v[120:123], v[16:31]
	v_mfma_f32_32x32x16_bf16 v[0:15], v[116:119], v[124:127], v[0:15]
	ds_read_b128 v[116:119], v92 offset:16384
	ds_read_b128 v[120:123], v93 offset:49152
	ds_read_b128 v[124:127], v93 offset:53248
	s_waitcnt lgkmcnt(1)
	v_mfma_f32_32x32x16_bf16 v[48:63], v[116:119], v[120:123], v[48:63]
	s_waitcnt lgkmcnt(0)
	v_mfma_f32_32x32x16_bf16 v[32:47], v[116:119], v[124:127], v[32:47]
	ds_read_b128 v[116:119], v92 offset:20480
	s_waitcnt lgkmcnt(0)
	v_mfma_f32_32x32x16_bf16 v[16:31], v[116:119], v[120:123], v[16:31]
	v_mfma_f32_32x32x16_bf16 v[0:15], v[116:119], v[124:127], v[0:15]
	ds_read_b128 v[116:119], v90 offset:16384
	ds_read_b128 v[120:123], v91 offset:49152
	ds_read_b128 v[124:127], v91 offset:53248
	s_waitcnt lgkmcnt(1)
	v_mfma_f32_32x32x16_bf16 v[48:63], v[116:119], v[120:123], v[48:63]
	s_waitcnt lgkmcnt(0)
	v_mfma_f32_32x32x16_bf16 v[32:47], v[116:119], v[124:127], v[32:47]
	ds_read_b128 v[116:119], v90 offset:20480
	s_waitcnt lgkmcnt(0)
	v_mfma_f32_32x32x16_bf16 v[16:31], v[116:119], v[120:123], v[16:31]
	v_mfma_f32_32x32x16_bf16 v[0:15], v[116:119], v[124:127], v[0:15]
	ds_read_b128 v[116:119], v88 offset:16384
	ds_read_b128 v[120:123], v89 offset:49152
	ds_read_b128 v[124:127], v89 offset:53248
	s_waitcnt lgkmcnt(1)
	v_mfma_f32_32x32x16_bf16 v[48:63], v[116:119], v[120:123], v[48:63]
	s_waitcnt lgkmcnt(0)
	v_mfma_f32_32x32x16_bf16 v[32:47], v[116:119], v[124:127], v[32:47]
	ds_read_b128 v[116:119], v88 offset:20480
	s_waitcnt vmcnt(13)
	ds_write_b128 v87, v[136:139]
	ds_write_b128 v87, v[128:131] offset:4096
	ds_write_b128 v87, v[132:135] offset:8192
	s_waitcnt vmcnt(11)
	ds_write_b128 v87, v[144:147] offset:12288
	ds_write_b128 v87, v[140:143] offset:32768
	s_waitcnt vmcnt(10)
	ds_write_b128 v87, v[148:151] offset:36864
	s_waitcnt vmcnt(9)
	ds_write_b128 v87, v[152:155] offset:40960
	s_waitcnt vmcnt(8)
	ds_write_b128 v87, v[156:159] offset:45056
	s_waitcnt lgkmcnt(0)
	s_barrier
	v_mfma_f32_32x32x16_bf16 v[16:31], v[116:119], v[120:123], v[16:31]
	v_mfma_f32_32x32x16_bf16 v[0:15], v[116:119], v[124:127], v[0:15]
	ds_read_b128 v[116:119], v94
	ds_read_b128 v[120:123], v95 offset:32768
	ds_read_b128 v[124:127], v95 offset:36864
	s_waitcnt lgkmcnt(1)
	v_mfma_f32_32x32x16_bf16 v[48:63], v[116:119], v[120:123], v[48:63]
	s_waitcnt lgkmcnt(0)
	v_mfma_f32_32x32x16_bf16 v[32:47], v[116:119], v[124:127], v[32:47]
	ds_read_b128 v[116:119], v94 offset:4096
	s_waitcnt lgkmcnt(0)
	v_mfma_f32_32x32x16_bf16 v[16:31], v[116:119], v[120:123], v[16:31]
	v_mfma_f32_32x32x16_bf16 v[0:15], v[116:119], v[124:127], v[0:15]
	ds_read_b128 v[116:119], v92
	ds_read_b128 v[120:123], v93 offset:32768
	ds_read_b128 v[124:127], v93 offset:36864
	s_waitcnt lgkmcnt(1)
	v_mfma_f32_32x32x16_bf16 v[48:63], v[116:119], v[120:123], v[48:63]
	s_waitcnt lgkmcnt(0)
	v_mfma_f32_32x32x16_bf16 v[32:47], v[116:119], v[124:127], v[32:47]
	ds_read_b128 v[116:119], v92 offset:4096
	s_waitcnt lgkmcnt(0)
	v_mfma_f32_32x32x16_bf16 v[16:31], v[116:119], v[120:123], v[16:31]
	v_mfma_f32_32x32x16_bf16 v[0:15], v[116:119], v[124:127], v[0:15]
	ds_read_b128 v[116:119], v90
	ds_read_b128 v[120:123], v91 offset:32768
	ds_read_b128 v[124:127], v91 offset:36864
	s_waitcnt lgkmcnt(1)
	v_mfma_f32_32x32x16_bf16 v[48:63], v[116:119], v[120:123], v[48:63]
	s_waitcnt lgkmcnt(0)
	v_mfma_f32_32x32x16_bf16 v[32:47], v[116:119], v[124:127], v[32:47]
	ds_read_b128 v[116:119], v90 offset:4096
	s_waitcnt lgkmcnt(0)
	v_mfma_f32_32x32x16_bf16 v[16:31], v[116:119], v[120:123], v[16:31]
	v_mfma_f32_32x32x16_bf16 v[0:15], v[116:119], v[124:127], v[0:15]
	ds_read_b128 v[116:119], v88
	ds_read_b128 v[120:123], v89 offset:32768
	ds_read_b128 v[124:127], v89 offset:36864
	s_waitcnt lgkmcnt(1)
	v_mfma_f32_32x32x16_bf16 v[48:63], v[116:119], v[120:123], v[48:63]
	s_waitcnt lgkmcnt(0)
	v_mfma_f32_32x32x16_bf16 v[32:47], v[116:119], v[124:127], v[32:47]
	ds_read_b128 v[116:119], v88 offset:4096
	s_waitcnt vmcnt(5)
	ds_write_b128 v87, v[100:103] offset:16384
	ds_write_b128 v87, v[96:99] offset:20480
	ds_write_b128 v87, v[70:73] offset:24576
	s_waitcnt vmcnt(3)
	ds_write_b128 v87, v[104:107] offset:28672
	ds_write_b128 v87, v[66:69] offset:49152
	s_waitcnt vmcnt(2)
	ds_write_b128 v87, v[74:77] offset:53248
	s_waitcnt vmcnt(1)
	ds_write_b128 v87, v[108:111] offset:57344
	s_waitcnt vmcnt(0)
	ds_write_b128 v87, v[112:115] offset:61440
	s_waitcnt lgkmcnt(0)
	s_barrier
	v_mfma_f32_32x32x16_bf16 v[16:31], v[116:119], v[120:123], v[16:31]
	v_mfma_f32_32x32x16_bf16 v[0:15], v[116:119], v[124:127], v[0:15]
	ds_read_b128 v[66:69], v94 offset:16384
	ds_read_b128 v[70:73], v95 offset:49152
	ds_read_b128 v[74:77], v95 offset:53248
	v_add_u32_e32 v64, s0, v64
	v_lshl_or_b32 v64, v86, 2, v64
	v_cmp_lt_i32_e64 s[82:83], s33, v64
	s_waitcnt lgkmcnt(1)
	v_mfma_f32_32x32x16_bf16 v[48:63], v[66:69], v[70:73], v[48:63]
	s_waitcnt lgkmcnt(0)
	v_mfma_f32_32x32x16_bf16 v[32:47], v[66:69], v[74:77], v[32:47]
	ds_read_b128 v[66:69], v94 offset:20480
	s_waitcnt lgkmcnt(0)
	v_mfma_f32_32x32x16_bf16 v[16:31], v[66:69], v[70:73], v[16:31]
	v_mfma_f32_32x32x16_bf16 v[0:15], v[66:69], v[74:77], v[0:15]
	ds_read_b128 v[66:69], v92 offset:16384
	ds_read_b128 v[70:73], v93 offset:49152
	ds_read_b128 v[74:77], v93 offset:53248
	s_waitcnt lgkmcnt(1)
	v_mfma_f32_32x32x16_bf16 v[48:63], v[66:69], v[70:73], v[48:63]
	s_waitcnt lgkmcnt(0)
	v_mfma_f32_32x32x16_bf16 v[32:47], v[66:69], v[74:77], v[32:47]
	ds_read_b128 v[66:69], v92 offset:20480
	s_waitcnt lgkmcnt(0)
	v_mfma_f32_32x32x16_bf16 v[16:31], v[66:69], v[70:73], v[16:31]
	v_mfma_f32_32x32x16_bf16 v[0:15], v[66:69], v[74:77], v[0:15]
	ds_read_b128 v[66:69], v90 offset:16384
	ds_read_b128 v[70:73], v91 offset:49152
	ds_read_b128 v[74:77], v91 offset:53248
	s_waitcnt lgkmcnt(1)
	v_mfma_f32_32x32x16_bf16 v[48:63], v[66:69], v[70:73], v[48:63]
	s_waitcnt lgkmcnt(0)
	v_mfma_f32_32x32x16_bf16 v[32:47], v[66:69], v[74:77], v[32:47]
	ds_read_b128 v[66:69], v90 offset:20480
	s_waitcnt lgkmcnt(0)
	v_mfma_f32_32x32x16_bf16 v[16:31], v[66:69], v[70:73], v[16:31]
	v_mfma_f32_32x32x16_bf16 v[0:15], v[66:69], v[74:77], v[0:15]
	ds_read_b128 v[66:69], v88 offset:16384
	ds_read_b128 v[70:73], v89 offset:49152
	ds_read_b128 v[74:77], v89 offset:53248
	ds_read_b128 v[88:91], v88 offset:20480
	s_waitcnt lgkmcnt(0)
	s_barrier
	v_mfma_f32_32x32x16_bf16 v[48:63], v[66:69], v[70:73], v[48:63]
	v_mfma_f32_32x32x16_bf16 v[32:47], v[66:69], v[74:77], v[32:47]
	v_mfma_f32_32x32x16_bf16 v[16:31], v[88:91], v[70:73], v[16:31]
	v_mfma_f32_32x32x16_bf16 v[0:15], v[88:91], v[74:77], v[0:15]
	v_lshrrev_b32_e32 v92, 6, v218
	v_and_b32_e32 v90, 31, v218
	v_readfirstlane_b32 s2, v92
	v_lshlrev_b32_e32 v90, 2, v90
	v_bfe_u32 v91, v218, 5, 1
	v_readlane_b32 s34, v252, 27
	v_readlane_b32 s35, v252, 28
	v_readlane_b32 s36, v250, 3
	v_readlane_b32 s37, v250, 4
	v_lshl_or_b32 v82, v91, 14, v90
	v_add_u32_e32 v83, 0x1000, v82
	v_add_u32_e32 v84, 0x2000, v82
	v_add_u32_e32 v85, 0x3000, v82
	v_add_u32_e32 v86, 0x8000, v82
	v_add_u32_e32 v87, 0x9000, v82
	v_add_u32_e32 v88, 0xa000, v82
	v_add_u32_e32 v89, 0xb000, v82
	s_lshr_b32 s3, s2, 1
	s_and_b32 s2, s2, 1
	s_lshl_b32 s3, s3, 6
	s_lshl_b32 s2, s2, 6
	s_add_i32 s5, s0, s3
	s_add_i32 s6, s4, s2
	s_lshl_b32 s6, s6, 2
	s_sub_i32 s7, 0x40a0, s5
	s_ashr_i32 s7, s7, 4
	s_max_i32 s7, s7, 0
	s_min_i32 s7, s7, 4
	s_add_i32 s24, s5, 0
	s_cmp_ge_u32 s24, 0x2010
	s_cselect_b32 s25, 32, 16
	s_cselect_b32 s26, 0x10000, 0
	s_cselect_b32 s27, 0x2010, 0
	s_sub_i32 s28, s24, s25
	s_lshl_b32 s28, s28, 12
	s_sub_i32 s27, s24, s27
	s_add_u32 s8, s60, s28
	s_addc_u32 s9, s61, 0
	s_add_u32 s10, s34, s28
	s_addc_u32 s11, s35, 0
	s_cmp_lg_u32 s27, 0
	s_cbranch_scc1 .Lepi1_nm0
	s_mov_b64 s[8:9], s[74:75]
	s_add_u32 s10, s36, s26
	s_addc_u32 s11, s37, 0
.Lepi1_nm0:
	s_cmp_lt_u32 s24, 0x4020
	s_cbranch_scc1 .Lepi1_dn0
	s_sub_i32 s28, s24, 0x4020
	s_lshl_b32 s28, s28, 12
	s_add_u32 s8, s62, s28
	s_addc_u32 s9, s63, 0
	s_add_u32 s10, s96, s28
	s_addc_u32 s11, s97, 0
	s_cmp_lt_u32 s24, 0x40a0
	s_cbranch_scc1 .Lepi1_dn0
	s_mov_b64 s[8:9], s[62:63]
	s_mov_b64 s[10:11], s[96:97]
.Lepi1_dn0:
	s_add_u32 s8, s8, s6
	s_addc_u32 s9, s9, 0
	s_add_u32 s10, s10, s6
	s_addc_u32 s11, s11, 0
	s_add_i32 s24, s5, 16
	s_cmp_ge_u32 s24, 0x2010
	s_cselect_b32 s25, 32, 16
	s_cselect_b32 s26, 0x10000, 0
	s_cselect_b32 s27, 0x2010, 0
	s_sub_i32 s28, s24, s25
	s_lshl_b32 s28, s28, 12
	s_sub_i32 s27, s24, s27
	s_add_u32 s12, s60, s28
	s_addc_u32 s13, s61, 0
	s_add_u32 s14, s34, s28
	s_addc_u32 s15, s35, 0
	s_cmp_lg_u32 s27, 0
	s_cbranch_scc1 .Lepi1_nm1
	s_mov_b64 s[12:13], s[74:75]
	s_add_u32 s14, s36, s26
	s_addc_u32 s15, s37, 0
.Lepi1_nm1:
	s_cmp_lt_u32 s24, 0x4020
	s_cbranch_scc1 .Lepi1_dn1
	s_sub_i32 s28, s24, 0x4020
	s_lshl_b32 s28, s28, 12
	s_add_u32 s12, s62, s28
	s_addc_u32 s13, s63, 0
	s_add_u32 s14, s96, s28
	s_addc_u32 s15, s97, 0
	s_cmp_lt_u32 s24, 0x40a0
	s_cbranch_scc1 .Lepi1_dn1
	s_mov_b64 s[12:13], s[62:63]
	s_mov_b64 s[14:15], s[96:97]
.Lepi1_dn1:
	s_add_u32 s12, s12, s6
	s_addc_u32 s13, s13, 0
	s_add_u32 s14, s14, s6
	s_addc_u32 s15, s15, 0
	s_add_i32 s24, s5, 32
	s_cmp_ge_u32 s24, 0x2010
	s_cselect_b32 s25, 32, 16
	s_cselect_b32 s26, 0x10000, 0
	s_cselect_b32 s27, 0x2010, 0
	s_sub_i32 s28, s24, s25
	s_lshl_b32 s28, s28, 12
	s_sub_i32 s27, s24, s27
	s_add_u32 s16, s60, s28
	s_addc_u32 s17, s61, 0
	s_add_u32 s18, s34, s28
	s_addc_u32 s19, s35, 0
	s_cmp_lg_u32 s27, 0
	s_cbranch_scc1 .Lepi1_nm2
	s_mov_b64 s[16:17], s[74:75]
	s_add_u32 s18, s36, s26
	s_addc_u32 s19, s37, 0
.Lepi1_nm2:
	s_cmp_lt_u32 s24, 0x4020
	s_cbranch_scc1 .Lepi1_dn2
	s_sub_i32 s28, s24, 0x4020
	s_lshl_b32 s28, s28, 12
	s_add_u32 s16, s62, s28
	s_addc_u32 s17, s63, 0
	s_add_u32 s18, s96, s28
	s_addc_u32 s19, s97, 0
	s_cmp_lt_u32 s24, 0x40a0
	s_cbranch_scc1 .Lepi1_dn2
	s_mov_b64 s[16:17], s[62:63]
	s_mov_b64 s[18:19], s[96:97]
.Lepi1_dn2:
	s_add_u32 s16, s16, s6
	s_addc_u32 s17, s17, 0
	s_add_u32 s18, s18, s6
	s_addc_u32 s19, s19, 0
	s_add_i32 s24, s5, 48
	s_cmp_ge_u32 s24, 0x2010
	s_cselect_b32 s25, 32, 16
	s_cselect_b32 s26, 0x10000, 0
	s_cselect_b32 s27, 0x2010, 0
	s_sub_i32 s28, s24, s25
	s_lshl_b32 s28, s28, 12
	s_sub_i32 s27, s24, s27
	s_add_u32 s20, s60, s28
	s_addc_u32 s21, s61, 0
	s_add_u32 s22, s34, s28
	s_addc_u32 s23, s35, 0
	s_cmp_lg_u32 s27, 0
	s_cbranch_scc1 .Lepi1_nm3
	s_mov_b64 s[20:21], s[74:75]
	s_add_u32 s22, s36, s26
	s_addc_u32 s23, s37, 0
.Lepi1_nm3:
	s_cmp_lt_u32 s24, 0x4020
	s_cbranch_scc1 .Lepi1_dn3
	s_sub_i32 s28, s24, 0x4020
	s_lshl_b32 s28, s28, 12
	s_add_u32 s20, s62, s28
	s_addc_u32 s21, s63, 0
	s_add_u32 s22, s96, s28
	s_addc_u32 s23, s97, 0
	s_cmp_lt_u32 s24, 0x40a0
	s_cbranch_scc1 .Lepi1_dn3
	s_mov_b64 s[20:21], s[62:63]
	s_mov_b64 s[22:23], s[96:97]
.Lepi1_dn3:
	s_add_u32 s20, s20, s6
	s_addc_u32 s21, s21, 0
	s_add_u32 s22, s22, s6
	s_addc_u32 s23, s23, 0
	global_load_dword v96, v82, s[8:9] nt
	global_load_dword v97, v82, s[8:9] offset:128 nt
	global_load_dword v98, v83, s[8:9] nt
	global_load_dword v99, v83, s[8:9] offset:128 nt
	global_load_dword v100, v84, s[8:9] nt
	global_load_dword v101, v84, s[8:9] offset:128 nt
	global_load_dword v102, v85, s[8:9] nt
	global_load_dword v103, v85, s[8:9] offset:128 nt
	global_load_dword v104, v86, s[8:9] nt
	global_load_dword v105, v86, s[8:9] offset:128 nt
	global_load_dword v106, v87, s[8:9] nt
	global_load_dword v107, v87, s[8:9] offset:128 nt
	global_load_dword v108, v88, s[8:9] nt
	global_load_dword v109, v88, s[8:9] offset:128 nt
	global_load_dword v110, v89, s[8:9] nt
	global_load_dword v111, v89, s[8:9] offset:128 nt
	global_load_dword v112, v82, s[12:13] nt
	global_load_dword v113, v82, s[12:13] offset:128 nt
	global_load_dword v114, v83, s[12:13] nt
	global_load_dword v115, v83, s[12:13] offset:128 nt
	global_load_dword v116, v84, s[12:13] nt
	global_load_dword v117, v84, s[12:13] offset:128 nt
	global_load_dword v118, v85, s[12:13] nt
	global_load_dword v119, v85, s[12:13] offset:128 nt
	global_load_dword v120, v86, s[12:13] nt
	global_load_dword v121, v86, s[12:13] offset:128 nt
	global_load_dword v122, v87, s[12:13] nt
	global_load_dword v123, v87, s[12:13] offset:128 nt
	global_load_dword v124, v88, s[12:13] nt
	global_load_dword v125, v88, s[12:13] offset:128 nt
	global_load_dword v126, v89, s[12:13] nt
	global_load_dword v127, v89, s[12:13] offset:128 nt
	global_load_dword v128, v82, s[16:17] nt
	global_load_dword v129, v82, s[16:17] offset:128 nt
	global_load_dword v130, v83, s[16:17] nt
	global_load_dword v131, v83, s[16:17] offset:128 nt
	global_load_dword v132, v84, s[16:17] nt
	global_load_dword v133, v84, s[16:17] offset:128 nt
	global_load_dword v134, v85, s[16:17] nt
	global_load_dword v135, v85, s[16:17] offset:128 nt
	global_load_dword v136, v86, s[16:17] nt
	global_load_dword v137, v86, s[16:17] offset:128 nt
	global_load_dword v138, v87, s[16:17] nt
	global_load_dword v139, v87, s[16:17] offset:128 nt
	global_load_dword v140, v88, s[16:17] nt
	global_load_dword v141, v88, s[16:17] offset:128 nt
	global_load_dword v142, v89, s[16:17] nt
	global_load_dword v143, v89, s[16:17] offset:128 nt
	global_load_dword v144, v82, s[20:21] nt
	global_load_dword v145, v82, s[20:21] offset:128 nt
	global_load_dword v146, v83, s[20:21] nt
	global_load_dword v147, v83, s[20:21] offset:128 nt
	global_load_dword v148, v84, s[20:21] nt
	global_load_dword v149, v84, s[20:21] offset:128 nt
	global_load_dword v150, v85, s[20:21] nt
	global_load_dword v151, v85, s[20:21] offset:128 nt
	global_load_dword v152, v86, s[20:21] nt
	global_load_dword v153, v86, s[20:21] offset:128 nt
	global_load_dword v154, v87, s[20:21] nt
	global_load_dword v155, v87, s[20:21] offset:128 nt
	global_load_dword v156, v88, s[20:21] nt
	global_load_dword v157, v88, s[20:21] offset:128 nt
	global_load_dword v158, v89, s[20:21] nt
	global_load_dword v159, v89, s[20:21] offset:128 nt
	s_cmp_lt_u32 s7, 1
	s_cbranch_scc1 .Lepi1_end
	s_waitcnt vmcnt(48)
	v_add_f32_e32 v96, v96, v48
	global_store_dword v82, v96, s[10:11]
	v_add_f32_e32 v97, v97, v32
	global_store_dword v82, v97, s[10:11] offset:128
	v_add_f32_e32 v98, v98, v49
	global_store_dword v83, v98, s[10:11]
	v_add_f32_e32 v99, v99, v33
	global_store_dword v83, v99, s[10:11] offset:128
	v_add_f32_e32 v100, v100, v50
	global_store_dword v84, v100, s[10:11]
	v_add_f32_e32 v101, v101, v34
	global_store_dword v84, v101, s[10:11] offset:128
	v_add_f32_e32 v102, v102, v51
	global_store_dword v85, v102, s[10:11]
	v_add_f32_e32 v103, v103, v35
	global_store_dword v85, v103, s[10:11] offset:128
	v_add_f32_e32 v104, v104, v52
	global_store_dword v86, v104, s[10:11]
	v_add_f32_e32 v105, v105, v36
	global_store_dword v86, v105, s[10:11] offset:128
	v_add_f32_e32 v106, v106, v53
	global_store_dword v87, v106, s[10:11]
	v_add_f32_e32 v107, v107, v37
	global_store_dword v87, v107, s[10:11] offset:128
	v_add_f32_e32 v108, v108, v54
	global_store_dword v88, v108, s[10:11]
	v_add_f32_e32 v109, v109, v38
	global_store_dword v88, v109, s[10:11] offset:128
	v_add_f32_e32 v110, v110, v55
	global_store_dword v89, v110, s[10:11]
	v_add_f32_e32 v111, v111, v39
	global_store_dword v89, v111, s[10:11] offset:128
	s_cmp_lt_u32 s7, 2
	s_cbranch_scc1 .Lepi1_end
	s_waitcnt vmcnt(48)
	v_add_f32_e32 v112, v112, v56
	global_store_dword v82, v112, s[14:15]
	v_add_f32_e32 v113, v113, v40
	global_store_dword v82, v113, s[14:15] offset:128
	v_add_f32_e32 v114, v114, v57
	global_store_dword v83, v114, s[14:15]
	v_add_f32_e32 v115, v115, v41
	global_store_dword v83, v115, s[14:15] offset:128
	v_add_f32_e32 v116, v116, v58
	global_store_dword v84, v116, s[14:15]
	v_add_f32_e32 v117, v117, v42
	global_store_dword v84, v117, s[14:15] offset:128
	v_add_f32_e32 v118, v118, v59
	global_store_dword v85, v118, s[14:15]
	v_add_f32_e32 v119, v119, v43
	global_store_dword v85, v119, s[14:15] offset:128
	v_add_f32_e32 v120, v120, v60
	global_store_dword v86, v120, s[14:15]
	v_add_f32_e32 v121, v121, v44
	global_store_dword v86, v121, s[14:15] offset:128
	v_add_f32_e32 v122, v122, v61
	global_store_dword v87, v122, s[14:15]
	v_add_f32_e32 v123, v123, v45
	global_store_dword v87, v123, s[14:15] offset:128
	v_add_f32_e32 v124, v124, v62
	global_store_dword v88, v124, s[14:15]
	v_add_f32_e32 v125, v125, v46
	global_store_dword v88, v125, s[14:15] offset:128
	v_add_f32_e32 v126, v126, v63
	global_store_dword v89, v126, s[14:15]
	v_add_f32_e32 v127, v127, v47
	global_store_dword v89, v127, s[14:15] offset:128
	s_cmp_lt_u32 s7, 3
	s_cbranch_scc1 .Lepi1_end
	s_waitcnt vmcnt(48)
	v_add_f32_e32 v128, v128, v16
	global_store_dword v82, v128, s[18:19]
	v_add_f32_e32 v129, v129, v0
	global_store_dword v82, v129, s[18:19] offset:128
	v_add_f32_e32 v130, v130, v17
	global_store_dword v83, v130, s[18:19]
	v_add_f32_e32 v131, v131, v1
	global_store_dword v83, v131, s[18:19] offset:128
	v_add_f32_e32 v132, v132, v18
	global_store_dword v84, v132, s[18:19]
	v_add_f32_e32 v133, v133, v2
	global_store_dword v84, v133, s[18:19] offset:128
	v_add_f32_e32 v134, v134, v19
	global_store_dword v85, v134, s[18:19]
	v_add_f32_e32 v135, v135, v3
	global_store_dword v85, v135, s[18:19] offset:128
	v_add_f32_e32 v136, v136, v20
	global_store_dword v86, v136, s[18:19]
	v_add_f32_e32 v137, v137, v4
	global_store_dword v86, v137, s[18:19] offset:128
	v_add_f32_e32 v138, v138, v21
	global_store_dword v87, v138, s[18:19]
	v_add_f32_e32 v139, v139, v5
	global_store_dword v87, v139, s[18:19] offset:128
	v_add_f32_e32 v140, v140, v22
	global_store_dword v88, v140, s[18:19]
	v_add_f32_e32 v141, v141, v6
	global_store_dword v88, v141, s[18:19] offset:128
	v_add_f32_e32 v142, v142, v23
	global_store_dword v89, v142, s[18:19]
	v_add_f32_e32 v143, v143, v7
	global_store_dword v89, v143, s[18:19] offset:128
	s_cmp_lt_u32 s7, 4
	s_cbranch_scc1 .Lepi1_end
	s_waitcnt vmcnt(48)
	v_add_f32_e32 v144, v144, v24
	global_store_dword v82, v144, s[22:23]
	v_add_f32_e32 v145, v145, v8
	global_store_dword v82, v145, s[22:23] offset:128
	v_add_f32_e32 v146, v146, v25
	global_store_dword v83, v146, s[22:23]
	v_add_f32_e32 v147, v147, v9
	global_store_dword v83, v147, s[22:23] offset:128
	v_add_f32_e32 v148, v148, v26
	global_store_dword v84, v148, s[22:23]
	v_add_f32_e32 v149, v149, v10
	global_store_dword v84, v149, s[22:23] offset:128
	v_add_f32_e32 v150, v150, v27
	global_store_dword v85, v150, s[22:23]
	v_add_f32_e32 v151, v151, v11
	global_store_dword v85, v151, s[22:23] offset:128
	v_add_f32_e32 v152, v152, v28
	global_store_dword v86, v152, s[22:23]
	v_add_f32_e32 v153, v153, v12
	global_store_dword v86, v153, s[22:23] offset:128
	v_add_f32_e32 v154, v154, v29
	global_store_dword v87, v154, s[22:23]
	v_add_f32_e32 v155, v155, v13
	global_store_dword v87, v155, s[22:23] offset:128
	v_add_f32_e32 v156, v156, v30
	global_store_dword v88, v156, s[22:23]
	v_add_f32_e32 v157, v157, v14
	global_store_dword v88, v157, s[22:23] offset:128
	v_add_f32_e32 v158, v158, v31
	global_store_dword v89, v158, s[22:23]
	v_add_f32_e32 v159, v159, v15
	global_store_dword v89, v159, s[22:23] offset:128
.Lepi1_end:
	s_branch .LBB0_781
